# S5 scan passes: each packed complex FMA split into two v_fma_f32 (same IEEE fused ops) and the op_sel wait-state nops between them dropped
# speedup vs baseline: 1.0021x; 1.0021x over previous
; #define LAS __attribute__((address_space(3)))
; __device__ __forceinline__ unsigned pk2(float lo, float hi) { return pg8::cvt_pk_bf16(lo, hi); }
; template <bool PASS_B> __device__ __forceinline__ void ssm_unit(const Args& a, LAS unsigned char* lds, const SsmTab& T, const u32x4 (&pre)[2], int l, size_t row0, int ntok, int gq, float& hr_io, float& hi_io, int wave) {
;     ...
;     for (int t0 = 0; t0 < ntok; t0 += 16) {
;         const int nt = (ntok - t0) < 16 ? (ntok - t0) : 16;
;         {
;             const bf16x8 uv = *(const LAS bf16x8*)(Ub + (t0 + r) * UST + wave * 16 + 8 * (qd & 1)); const bf16x8 ub = qd < 2 ? uv : (bf16x8){0, 0, 0, 0, 0, 0, 0, 0};
; #pragma unroll
;             for (int pt = 0; pt < 8; ++pt) { const f32x4 x = __builtin_amdgcn_mfma_f32_16x16x32_bf16(T.af[pt], ub, (f32x4){0.f, 0.f, 0.f, 0.f}, 0, 0, 0); *(LAS f32x4*)(Xs + r * XST + pt * 16 + 4 * qd) = x; }
;         }
;         asm volatile("s_waitcnt lgkmcnt(0)" ::: "memory");
;         {
;             typedef float f32x2 __attribute__((ext_vector_type(2)));
;             f32x2 xv[16];
; #pragma unroll
;             for (int tt = 0; tt < 16; ++tt) xv[tt] = *(const LAS f32x2*)(Xs + tt * XST + 2 * lane);
;             f32x2 h = {hr, hi}; const f32x2 a1 = {ar, ar}, a2 = {-ai, ai};
;             if (nt == 16) {
; #pragma unroll
;                 for (int tt = 0; tt < 16; ++tt) { const f32x2 hs = {h.y, h.x}; h = a1 * h + (a2 * hs + xv[tt]);
;                     if (PASS_B) *(LAS unsigned*)(hb + tt * HST + 2 * lane) = pk2(h.x, h.y); }
;             } else {
; #pragma unroll
;                 for (int tt = 0; tt < 16; ++tt) if (tt < nt) { const f32x2 hs = {h.y, h.x}; h = a1 * h + (a2 * hs + xv[tt]);
;                     if (PASS_B) *(LAS unsigned*)(hb + tt * HST + 2 * lane) = pk2(h.x, h.y); }
;             }
;             hr = h.x; hi = h.y;
.LBB0_355:
	s_or_b64 exec, exec, s[14:15]
	s_waitcnt lgkmcnt(0)
	v_mfma_f32_16x16x32_bf16 v[64:67], v[34:37], v[20:23], 0
	v_add_u32_e32 v26, 0x4800, v25
	s_add_i32 s16, s16, 16
	s_cmp_lt_u32 s16, 48
	v_mfma_f32_16x16x32_bf16 v[68:71], v[38:41], v[20:23], 0
	v_add_u32_e32 v0, 0x1100, v0
	s_nop 2
	ds_write_b128 v24, v[64:67] offset:17408
	v_mfma_f32_16x16x32_bf16 v[72:75], v[30:33], v[20:23], 0
	v_mfma_f32_16x16x32_bf16 v[76:79], v[42:45], v[20:23], 0
	s_nop 0
	ds_write_b128 v24, v[68:71] offset:17472
	s_nop 4
	ds_write_b128 v24, v[72:75] offset:17536
	ds_write_b128 v24, v[76:79] offset:17600
	v_mfma_f32_16x16x32_bf16 v[80:83], v[50:53], v[20:23], 0
	v_mfma_f32_16x16x32_bf16 v[64:67], v[54:57], v[20:23], 0
	v_mfma_f32_16x16x32_bf16 v[68:71], v[46:49], v[20:23], 0
	s_nop 5
	ds_write_b128 v24, v[80:83] offset:17664
	ds_write_b128 v24, v[64:67] offset:17728
	ds_write_b128 v24, v[68:71] offset:17792
	v_mfma_f32_16x16x32_bf16 v[20:23], v[58:61], v[20:23], 0
	s_nop 7
	ds_write_b128 v24, v[20:23] offset:17856
	s_waitcnt lgkmcnt(0)
	v_add_u32_e32 v20, 0x4000, v25
	ds_read2_b64 v[20:23], v20 offset0:128 offset1:194
	ds_read2_b64 v[64:67], v26 offset0:4 offset1:70
	ds_read2_b64 v[68:71], v26 offset0:136 offset1:202
	v_add_u32_e32 v26, 0x5000, v25
	ds_read2_b64 v[72:75], v26 offset0:12 offset1:78
	ds_read2_b64 v[76:79], v26 offset0:144 offset1:210
	v_add_u32_e32 v26, 0x5800, v25
	s_waitcnt lgkmcnt(4)
	v_fma_f32 v20, v28, v63, v20
	v_fma_f32 v21, v29, v62, v21
	ds_read2_b64 v[80:83], v26 offset0:20 offset1:86
	ds_read2_b64 v[84:87], v26 offset0:152 offset1:218
	v_fma_f32 v20, v2, v62, v20
	v_fma_f32 v21, v3, v63, v21
	v_add_u32_e32 v26, 0x6000, v25
	v_fma_f32 v22, v28, v21, v22
	v_fma_f32 v23, v29, v20, v23
	ds_read2_b64 v[88:91], v26 offset0:28 offset1:94
	v_fma_f32 v20, v2, v20, v22
	v_fma_f32 v21, v3, v21, v23
	s_waitcnt lgkmcnt(0)
	s_waitcnt lgkmcnt(6)
	v_fma_f32 v22, v28, v21, v64
	v_fma_f32 v23, v29, v20, v65
	v_fma_f32 v20, v2, v20, v22
	v_fma_f32 v21, v3, v21, v23
	v_fma_f32 v22, v28, v21, v66
	v_fma_f32 v23, v29, v20, v67
	v_fma_f32 v20, v2, v20, v22
	v_fma_f32 v21, v3, v21, v23
	s_waitcnt lgkmcnt(5)
	v_fma_f32 v22, v28, v21, v68
	v_fma_f32 v23, v29, v20, v69
	v_fma_f32 v20, v2, v20, v22
	v_fma_f32 v21, v3, v21, v23
	v_fma_f32 v22, v28, v21, v70
	v_fma_f32 v23, v29, v20, v71
	v_fma_f32 v20, v2, v20, v22
	v_fma_f32 v21, v3, v21, v23
	s_waitcnt lgkmcnt(4)
	v_fma_f32 v22, v28, v21, v72
	v_fma_f32 v23, v29, v20, v73
	v_fma_f32 v20, v2, v20, v22
	v_fma_f32 v21, v3, v21, v23
	v_fma_f32 v22, v28, v21, v74
	v_fma_f32 v23, v29, v20, v75
	v_fma_f32 v20, v2, v20, v22
	v_fma_f32 v21, v3, v21, v23
	s_waitcnt lgkmcnt(3)
	v_fma_f32 v22, v28, v21, v76
	v_fma_f32 v23, v29, v20, v77
	v_fma_f32 v20, v2, v20, v22
	v_fma_f32 v21, v3, v21, v23
	v_fma_f32 v22, v28, v21, v78
	v_fma_f32 v23, v29, v20, v79
	v_fma_f32 v20, v2, v20, v22
	v_fma_f32 v21, v3, v21, v23
	s_waitcnt lgkmcnt(2)
	v_fma_f32 v22, v28, v21, v80
	v_fma_f32 v23, v29, v20, v81
	v_fma_f32 v20, v2, v20, v22
	v_fma_f32 v21, v3, v21, v23
	v_fma_f32 v22, v28, v21, v82
	v_fma_f32 v23, v29, v20, v83
	v_fma_f32 v20, v2, v20, v22
	v_fma_f32 v21, v3, v21, v23
	s_waitcnt lgkmcnt(1)
	v_fma_f32 v22, v28, v21, v84
	v_fma_f32 v23, v29, v20, v85
	v_fma_f32 v20, v2, v20, v22
	v_fma_f32 v21, v3, v21, v23
	v_fma_f32 v22, v28, v21, v86
	v_fma_f32 v23, v29, v20, v87
	v_fma_f32 v20, v2, v20, v22
	v_fma_f32 v21, v3, v21, v23
	s_waitcnt lgkmcnt(0)
	v_fma_f32 v22, v28, v21, v88
	v_fma_f32 v23, v29, v20, v89
	v_fma_f32 v20, v2, v20, v22
	v_fma_f32 v21, v3, v21, v23
	v_fma_f32 v22, v28, v21, v90
	v_fma_f32 v23, v29, v20, v91
	v_fma_f32 v62, v2, v20, v22
	v_fma_f32 v63, v3, v21, v23
	s_cbranch_scc0 .LBB0_358

; #define LAS __attribute__((address_space(3)))
; __device__ __forceinline__ unsigned pk2(float lo, float hi) { return pg8::cvt_pk_bf16(lo, hi); }
; template <bool PASS_B> __device__ __forceinline__ void ssm_unit(const Args& a, LAS unsigned char* lds, const SsmTab& T, const u32x4 (&pre)[2], int l, size_t row0, int ntok, int gq, float& hr_io, float& hi_io, int wave) {
;     ...
;         {
;             const bf16x8 uv = *(const LAS bf16x8*)(Ub + (t0 + r) * UST + wave * 16 + 8 * (qd & 1)); const bf16x8 ub = qd < 2 ? uv : (bf16x8){0, 0, 0, 0, 0, 0, 0, 0};
; #pragma unroll
;             for (int pt = 0; pt < 8; ++pt) { const f32x4 x = __builtin_amdgcn_mfma_f32_16x16x32_bf16(T.af[pt], ub, (f32x4){0.f, 0.f, 0.f, 0.f}, 0, 0, 0); *(LAS f32x4*)(Xs + r * XST + pt * 16 + 4 * qd) = x; }
;         }
;         asm volatile("s_waitcnt lgkmcnt(0)" ::: "memory");
;         {
;             typedef float f32x2 __attribute__((ext_vector_type(2)));
;             f32x2 xv[16];
; #pragma unroll
;             for (int tt = 0; tt < 16; ++tt) xv[tt] = *(const LAS f32x2*)(Xs + tt * XST + 2 * lane);
;             f32x2 h = {hr, hi}; const f32x2 a1 = {ar, ar}, a2 = {-ai, ai};
;             if (nt == 16) {
; #pragma unroll
;                 for (int tt = 0; tt < 16; ++tt) { const f32x2 hs = {h.y, h.x}; h = a1 * h + (a2 * hs + xv[tt]);
;                     if (PASS_B) *(LAS unsigned*)(hb + tt * HST + 2 * lane) = pk2(h.x, h.y); }
;             } else {
; #pragma unroll
;                 for (int tt = 0; tt < 16; ++tt) if (tt < nt) { const f32x2 hs = {h.y, h.x}; h = a1 * h + (a2 * hs + xv[tt]);
;                     if (PASS_B) *(LAS unsigned*)(hb + tt * HST + 2 * lane) = pk2(h.x, h.y); }
;             }
;             hr = h.x; hi = h.y;
.LBB0_469:
	s_or_b64 exec, exec, s[8:9]
	s_waitcnt lgkmcnt(0)
	v_mfma_f32_16x16x32_bf16 v[94:97], v[32:35], v[12:15], 0
	v_add_u32_e32 v87, 0x5800, v84
	s_add_i32 s10, s10, 16
	s_mov_b64 s[8:9], 0x4000
	v_mfma_f32_16x16x32_bf16 v[98:101], v[36:39], v[12:15], 0
	v_add_u32_e32 v19, 0x1100, v19
	s_nop 2
	ds_write_b128 v0, v[94:97] offset:17408
	s_cmp_lt_u32 s10, 48
	v_mfma_f32_16x16x32_bf16 v[102:105], v[28:31], v[12:15], 0
	v_mfma_f32_16x16x32_bf16 v[106:109], v[40:43], v[12:15], 0
	ds_write_b128 v0, v[98:101] offset:17472
	s_nop 5
	ds_write_b128 v0, v[102:105] offset:17536
	ds_write_b128 v0, v[106:109] offset:17600
	v_mfma_f32_16x16x32_bf16 v[110:113], v[48:51], v[12:15], 0
	v_mfma_f32_16x16x32_bf16 v[94:97], v[52:55], v[12:15], 0
	v_mfma_f32_16x16x32_bf16 v[98:101], v[44:47], v[12:15], 0
	s_nop 5
	ds_write_b128 v0, v[110:113] offset:17664
	ds_write_b128 v0, v[94:97] offset:17728
	ds_write_b128 v0, v[98:101] offset:17792
	v_mfma_f32_16x16x32_bf16 v[12:15], v[56:59], v[12:15], 0
	s_nop 7
	ds_write_b128 v0, v[12:15] offset:17856
	s_waitcnt lgkmcnt(0)
	v_add_u32_e32 v12, 0x4000, v84
	ds_read2_b64 v[12:15], v12 offset0:128 offset1:194
	ds_read2_b64 v[94:97], v87 offset0:152 offset1:218
	ds_read2_b64 v[98:101], v87 offset0:20 offset1:86
	v_add_u32_e32 v87, 0x5000, v84
	ds_read2_b64 v[102:105], v87 offset0:144 offset1:210
	ds_read2_b64 v[106:109], v87 offset0:12 offset1:78
	v_add_u32_e32 v87, 0x4800, v84
	ds_read2_b64 v[110:113], v87 offset0:136 offset1:202
	ds_read2_b64 v[114:117], v87 offset0:4 offset1:70
	s_waitcnt lgkmcnt(6)
	v_fma_f32 v12, v2, v83, v12
	v_fma_f32 v13, v3, v82, v13
	v_add_u32_e32 v87, 0x6000, v84
	v_fma_f32 v12, v80, v82, v12
	v_fma_f32 v13, v81, v83, v13
	ds_read2_b64 v[118:121], v87 offset0:28 offset1:94
	v_fma_f32 v14, v2, v13, v14
	v_fma_f32 v15, v3, v12, v15
	v_cvt_pk_bf16_f32 v82, v12, v13
	ds_write_b32 v85, v82
	v_fma_f32 v12, v80, v12, v14
	v_fma_f32 v13, v81, v13, v15
	s_nop 0
	v_cvt_pk_bf16_f32 v14, v12, v13
	ds_write_b32 v85, v14 offset:272
	s_waitcnt lgkmcnt(3)
	v_fma_f32 v14, v2, v13, v114
	v_fma_f32 v15, v3, v12, v115
	v_fma_f32 v12, v80, v12, v14
	v_fma_f32 v13, v81, v13, v15
	s_nop 0
	v_cvt_pk_bf16_f32 v14, v12, v13
	ds_write_b32 v85, v14 offset:544
	v_fma_f32 v14, v2, v13, v116
	v_fma_f32 v15, v3, v12, v117
	v_fma_f32 v12, v80, v12, v14
	v_fma_f32 v13, v81, v13, v15
	s_nop 0
	v_cvt_pk_bf16_f32 v14, v12, v13
	ds_write_b32 v85, v14 offset:816
	v_fma_f32 v14, v2, v13, v110
	v_fma_f32 v15, v3, v12, v111
	v_fma_f32 v12, v80, v12, v14
	v_fma_f32 v13, v81, v13, v15
	s_nop 0
	v_cvt_pk_bf16_f32 v14, v12, v13
	ds_write_b32 v85, v14 offset:1088
	v_fma_f32 v14, v2, v13, v112
	v_fma_f32 v15, v3, v12, v113
	v_fma_f32 v12, v80, v12, v14
	v_fma_f32 v13, v81, v13, v15
	s_nop 0
	v_cvt_pk_bf16_f32 v14, v12, v13
	ds_write_b32 v85, v14 offset:1360
	v_fma_f32 v14, v2, v13, v106
	v_fma_f32 v15, v3, v12, v107
	v_fma_f32 v12, v80, v12, v14
	v_fma_f32 v13, v81, v13, v15
	s_nop 0
	v_cvt_pk_bf16_f32 v14, v12, v13
	ds_write_b32 v85, v14 offset:1632
	v_fma_f32 v14, v2, v13, v108
	v_fma_f32 v15, v3, v12, v109
	v_fma_f32 v12, v80, v12, v14
	v_fma_f32 v13, v81, v13, v15
	s_nop 0
	v_cvt_pk_bf16_f32 v14, v12, v13
	ds_write_b32 v85, v14 offset:1904
	v_fma_f32 v14, v2, v13, v102
	v_fma_f32 v15, v3, v12, v103
	v_fma_f32 v12, v80, v12, v14
	v_fma_f32 v13, v81, v13, v15
	s_nop 0
	v_cvt_pk_bf16_f32 v14, v12, v13
	ds_write_b32 v85, v14 offset:2176
	v_fma_f32 v14, v2, v13, v104
	v_fma_f32 v15, v3, v12, v105
	v_fma_f32 v12, v80, v12, v14
	v_fma_f32 v13, v81, v13, v15
	s_nop 0
	v_cvt_pk_bf16_f32 v14, v12, v13
	ds_write_b32 v85, v14 offset:2448
	v_fma_f32 v14, v2, v13, v98
	v_fma_f32 v15, v3, v12, v99
	v_fma_f32 v12, v80, v12, v14
	v_fma_f32 v13, v81, v13, v15
	s_nop 0
	v_cvt_pk_bf16_f32 v14, v12, v13
	ds_write_b32 v85, v14 offset:2720
	v_fma_f32 v14, v2, v13, v100
	v_fma_f32 v15, v3, v12, v101
	v_fma_f32 v12, v80, v12, v14
	v_fma_f32 v13, v81, v13, v15
	s_nop 0
	v_cvt_pk_bf16_f32 v14, v12, v13
	ds_write_b32 v85, v14 offset:2992
	v_fma_f32 v14, v2, v13, v94
	v_fma_f32 v15, v3, v12, v95
	v_fma_f32 v12, v80, v12, v14
	v_fma_f32 v13, v81, v13, v15
	s_nop 0
	v_cvt_pk_bf16_f32 v14, v12, v13
	ds_write_b32 v85, v14 offset:3264
	v_fma_f32 v14, v2, v13, v96
	v_fma_f32 v15, v3, v12, v97
	v_fma_f32 v12, v80, v12, v14
	v_fma_f32 v13, v81, v13, v15
	s_nop 0
	v_cvt_pk_bf16_f32 v14, v12, v13
	ds_write_b32 v85, v14 offset:3536
	s_waitcnt lgkmcnt(14)
; #define LAS __attribute__((address_space(3)))
; __device__ __forceinline__ float bf2f(unsigned short b) { return __uint_as_float(((unsigned)b) << 16); }
; __device__ __forceinline__ unsigned pk2(float lo, float hi) { return pg8::cvt_pk_bf16(lo, hi); }
; __device__ __forceinline__ unsigned short f2bf(float f) { return (unsigned short)(pg8::cvt_pk_bf16(f, 0.f) & 0xffffu); }
; template <bool PASS_B> __device__ __forceinline__ void ssm_unit(const Args& a, LAS unsigned char* lds, const SsmTab& T, const u32x4 (&pre)[2], int l, size_t row0, int ntok, int gq, float& hr_io, float& hi_io, int wave) {
;     ...
;                 for (int tt = 0; tt < 16; ++tt) { const f32x2 hs = {h.y, h.x}; h = a1 * h + (a2 * hs + xv[tt]);
;                     if (PASS_B) *(LAS unsigned*)(hb + tt * HST + 2 * lane) = pk2(h.x, h.y); }
;             } else {
; #pragma unroll
;                 for (int tt = 0; tt < 16; ++tt) if (tt < nt) { const f32x2 hs = {h.y, h.x}; h = a1 * h + (a2 * hs + xv[tt]);
;                     if (PASS_B) *(LAS unsigned*)(hb + tt * HST + 2 * lane) = pk2(h.x, h.y); }
;             }
;             hr = h.x; hi = h.y;
;         }
;         if (PASS_B) {
;             f32x4 acc = {0.f, 0.f, 0.f, 0.f};
;             asm volatile("s_waitcnt lgkmcnt(0)" ::: "memory");
; #pragma unroll
;             for (int s = 0; s < 4; ++s) { const bf16x8 hf = *(const LAS bf16x8*)(hb + r * HST + s * 32 + qd * 8); acc = __builtin_amdgcn_mfma_f32_16x16x32_bf16(hf, T.cf[s], acc, 0, 0, 0); }
;             asm volatile("s_waitcnt lgkmcnt(0)" ::: "memory");
;             bf16_t* yo = (bf16_t*)(a.ws + WS_B + HALFROWS);
; #pragma unroll
;             for (int k = 0; k < 4; ++k) { const int tt = 4 * qd + k;
;                 if (tt < nt) { const float y = acc[k] + dsk * bf2f(Ub[(t0 + tt) * UST + wave * 16 + r]); yo[(row0 + t0 + tt) * 512 + g * 16 + r] = f2bf(gelu_tanh(y)); } }
	v_fma_f32 v14, v2, v13, v118
	v_fma_f32 v15, v3, v12, v119
	v_fma_f32 v12, v80, v12, v14
	v_fma_f32 v13, v81, v13, v15
	s_nop 0
	v_cvt_pk_bf16_f32 v14, v12, v13
	ds_write_b32 v85, v14 offset:3808
	v_fma_f32 v14, v2, v13, v120
	v_fma_f32 v15, v3, v12, v121
	v_fma_f32 v82, v80, v12, v14
	v_fma_f32 v83, v81, v13, v15
	s_nop 0
	v_cvt_pk_bf16_f32 v12, v82, v83
	ds_write_b32 v85, v12 offset:4080
	s_waitcnt lgkmcnt(0)
	ds_read_b128 v[12:15], v86
	ds_read_b128 v[94:97], v86 offset:64
	s_waitcnt lgkmcnt(1)
	v_mfma_f32_16x16x32_bf16 v[12:15], v[12:15], v[60:63], 0
	ds_read_b128 v[98:101], v86 offset:128
	s_waitcnt lgkmcnt(1)
	v_mfma_f32_16x16x32_bf16 v[12:15], v[94:97], v[64:67], v[12:15]
	ds_read_b128 v[94:97], v86 offset:192
	s_waitcnt lgkmcnt(0)
	ds_read_u16 v87, v18
	s_waitcnt lgkmcnt(2)
	v_mfma_f32_16x16x32_bf16 v[12:15], v[98:101], v[68:71], v[12:15]
	s_waitcnt lgkmcnt(0)
	v_lshlrev_b32_e32 v87, 16, v87
	v_mfma_f32_16x16x32_bf16 v[12:15], v[94:97], v[72:75], v[12:15]
	s_nop 7
	v_fma_f32 v12, v90, v87, v12
	v_mul_f32_e32 v87, v12, v12
	v_fmamk_f32 v87, v87, 0xbdd2d3e7, v214
	v_mul_f32_e32 v87, v12, v87
	v_exp_f32_e32 v87, v87
	s_nop 0
	v_add_f32_e32 v87, 1.0, v87
	v_rcp_f32_e32 v87, v87
	s_nop 0
	v_mul_f32_e32 v12, v12, v87
	v_cvt_pk_bf16_f32 v12, v12, v1
	ds_read_u16 v87, v18 offset:272
	global_store_short v[16:17], v12, off offset:-2048
	s_waitcnt lgkmcnt(0)
	v_lshlrev_b32_e32 v87, 16, v87
	v_fma_f32 v13, v90, v87, v13
	v_mul_f32_e32 v87, v13, v13
	v_fmamk_f32 v87, v87, 0xbdd2d3e7, v214
	v_mul_f32_e32 v87, v13, v87
	v_exp_f32_e32 v87, v87
	s_nop 0
	v_add_f32_e32 v87, 1.0, v87
	v_rcp_f32_e32 v87, v87
	s_nop 0
	v_mul_f32_e32 v12, v13, v87
	v_cvt_pk_bf16_f32 v12, v12, v1
	ds_read_u16 v13, v18 offset:544
	global_store_short v[16:17], v12, off offset:-1024
	s_waitcnt lgkmcnt(0)
	v_lshlrev_b32_e32 v13, 16, v13
	v_fma_f32 v13, v90, v13, v14
	v_mul_f32_e32 v14, v13, v13
	v_fmamk_f32 v14, v14, 0xbdd2d3e7, v214
	v_mul_f32_e32 v14, v13, v14
	v_exp_f32_e32 v14, v14
	s_nop 0
	v_add_f32_e32 v14, 1.0, v14
	v_rcp_f32_e32 v14, v14
	s_nop 0
	v_mul_f32_e32 v12, v13, v14
	v_cvt_pk_bf16_f32 v12, v12, v1
	ds_read_u16 v13, v18 offset:816
	global_store_short v[16:17], v12, off
	v_add_u32_e32 v18, 0x1100, v18
	s_waitcnt lgkmcnt(0)
	v_lshlrev_b32_e32 v13, 16, v13
	v_fmac_f32_e32 v15, v90, v13
	v_mul_f32_e32 v13, v15, v15
	v_fmamk_f32 v13, v13, 0xbdd2d3e7, v214
	v_mul_f32_e32 v13, v15, v13
	v_exp_f32_e32 v13, v13
	s_nop 0
	v_add_f32_e32 v13, 1.0, v13
	v_rcp_f32_e32 v13, v13
	s_nop 0
	v_mul_f32_e32 v12, v15, v13
	v_cvt_pk_bf16_f32 v12, v12, v1
	global_store_short v[16:17], v12, off offset:1024
	s_waitcnt lgkmcnt(0)
	v_lshl_add_u64 v[16:17], v[16:17], 0, s[8:9]
	s_cbranch_scc0 .LBB0_472

; #define LAS __attribute__((address_space(3)))
; template <bool PASS_B> __device__ __forceinline__ void ssm_unit(const Args& a, LAS unsigned char* lds, const SsmTab& T, const u32x4 (&pre)[2], int l, size_t row0, int ntok, int gq, float& hr_io, float& hi_io, int wave) {
;     ...
;         {
;             const bf16x8 uv = *(const LAS bf16x8*)(Ub + (t0 + r) * UST + wave * 16 + 8 * (qd & 1)); const bf16x8 ub = qd < 2 ? uv : (bf16x8){0, 0, 0, 0, 0, 0, 0, 0};
; #pragma unroll
;             for (int pt = 0; pt < 8; ++pt) { const f32x4 x = __builtin_amdgcn_mfma_f32_16x16x32_bf16(T.af[pt], ub, (f32x4){0.f, 0.f, 0.f, 0.f}, 0, 0, 0); *(LAS f32x4*)(Xs + r * XST + pt * 16 + 4 * qd) = x; }
;         }
;         asm volatile("s_waitcnt lgkmcnt(0)" ::: "memory");
;         {
;             typedef float f32x2 __attribute__((ext_vector_type(2)));
;             f32x2 xv[16];
; #pragma unroll
;             for (int tt = 0; tt < 16; ++tt) xv[tt] = *(const LAS f32x2*)(Xs + tt * XST + 2 * lane);
;             f32x2 h = {hr, hi}; const f32x2 a1 = {ar, ar}, a2 = {-ai, ai};
;             if (nt == 16) {
; #pragma unroll
;                 for (int tt = 0; tt < 16; ++tt) { const f32x2 hs = {h.y, h.x}; h = a1 * h + (a2 * hs + xv[tt]);
;                     if (PASS_B) *(LAS unsigned*)(hb + tt * HST + 2 * lane) = pk2(h.x, h.y); }
;             } else {
; #pragma unroll
;                 for (int tt = 0; tt < 16; ++tt) if (tt < nt) { const f32x2 hs = {h.y, h.x}; h = a1 * h + (a2 * hs + xv[tt]);
;                     if (PASS_B) *(LAS unsigned*)(hb + tt * HST + 2 * lane) = pk2(h.x, h.y); }
;             }
;             hr = h.x; hi = h.y;
;         }
;         if (PASS_B) {
;             f32x4 acc = {0.f, 0.f, 0.f, 0.f};
;             asm volatile("s_waitcnt lgkmcnt(0)" ::: "memory");
; #pragma unroll
;             for (int s = 0; s < 4; ++s) { const bf16x8 hf = *(const LAS bf16x8*)(hb + r * HST + s * 32 + qd * 8); acc = __builtin_amdgcn_mfma_f32_16x16x32_bf16(hf, T.cf[s], acc, 0, 0, 0); }
;             asm volatile("s_waitcnt lgkmcnt(0)" ::: "memory");
;             bf16_t* yo = (bf16_t*)(a.ws + WS_B + HALFROWS);
; #pragma unroll
;             for (int k = 0; k < 4; ++k) { const int tt = 4 * qd + k;
;                 if (tt < nt) { const float y = acc[k] + dsk * bf2f(Ub[(t0 + tt) * UST + wave * 16 + r]); yo[(row0 + t0 + tt) * 512 + g * 16 + r] = f2bf(gelu_tanh(y)); } }
.LBB0_490:
	s_or_b64 exec, exec, s[8:9]
	v_and_b32_e32 v80, 63, v12
	v_and_b32_e32 v0, 15, v12
	v_cmp_gt_u32_e32 vcc, 32, v80
	v_and_b32_e32 v78, 48, v12
	v_mul_u32_u24_e32 v79, 0x110, v0
	v_mov_b32_e32 v12, 0
	v_mov_b32_e32 v13, 0
	v_mov_b32_e32 v14, 0
	v_mov_b32_e32 v15, 0
	s_waitcnt lgkmcnt(0)
	s_barrier
	s_and_saveexec_b64 s[8:9], vcc
	v_add3_u32 v12, s95, v78, v79
	ds_read_b128 v[12:15], v12
	s_or_b64 exec, exec, s[8:9]
	s_waitcnt lgkmcnt(0)
	v_mfma_f32_16x16x32_bf16 v[82:85], v[32:35], v[12:15], 0
	v_mul_u32_u24_e32 v81, 0x210, v0
	v_add3_u32 v81, s76, v81, v78
	v_add3_u32 v79, s77, v79, v78
	v_cmp_eq_u32_e32 vcc, 0, v78
	s_nop 3
	ds_write_b128 v81, v[82:85] offset:17408
	v_mfma_f32_16x16x32_bf16 v[82:85], v[36:39], v[12:15], 0
	s_nop 7
	ds_write_b128 v81, v[82:85] offset:17472
	v_mfma_f32_16x16x32_bf16 v[82:85], v[28:31], v[12:15], 0
	s_nop 7
	ds_write_b128 v81, v[82:85] offset:17536
	v_mfma_f32_16x16x32_bf16 v[82:85], v[40:43], v[12:15], 0
	s_nop 7
	ds_write_b128 v81, v[82:85] offset:17600
	v_mfma_f32_16x16x32_bf16 v[82:85], v[48:51], v[12:15], 0
	s_nop 7
	ds_write_b128 v81, v[82:85] offset:17664
	v_mfma_f32_16x16x32_bf16 v[82:85], v[52:55], v[12:15], 0
	s_nop 7
	ds_write_b128 v81, v[82:85] offset:17728
	v_mfma_f32_16x16x32_bf16 v[82:85], v[44:47], v[12:15], 0
	v_mfma_f32_16x16x32_bf16 v[12:15], v[56:59], v[12:15], 0
	s_nop 6
	ds_write_b128 v81, v[82:85] offset:17792
	ds_write_b128 v81, v[12:15] offset:17856
	v_lshl_add_u32 v81, v80, 3, s76
	s_waitcnt lgkmcnt(0)
	v_add_u32_e32 v12, 0x4000, v81
	ds_read2_b64 v[12:15], v12 offset0:128 offset1:194
	v_add_u32_e32 v81, 0x4800, v81
	ds_read2_b64 v[82:85], v81 offset0:4 offset1:70
	v_lshl_add_u32 v80, v80, 2, s77
	s_waitcnt vmcnt(0) lgkmcnt(1)
	v_fma_f32 v12, v2, v77, v12
	v_fma_f32 v13, v3, v76, v13
	v_fma_f32 v12, v16, v76, v12
	v_fma_f32 v13, v17, v77, v13
	v_fma_f32 v14, v2, v13, v14
	v_fma_f32 v15, v3, v12, v15
	v_cvt_pk_bf16_f32 v76, v12, v13
	ds_write_b32 v80, v76
	v_fma_f32 v12, v16, v12, v14
	v_fma_f32 v13, v17, v13, v15
	s_nop 0
	v_cvt_pk_bf16_f32 v14, v12, v13
	ds_write_b32 v80, v14 offset:272
	s_waitcnt lgkmcnt(2)
	v_fma_f32 v14, v2, v13, v82
	v_fma_f32 v15, v3, v12, v83
	v_fma_f32 v12, v16, v12, v14
	v_fma_f32 v13, v17, v13, v15
	s_nop 0
	v_cvt_pk_bf16_f32 v14, v12, v13
	ds_write_b32 v80, v14 offset:544
	v_fma_f32 v14, v2, v13, v84
	v_fma_f32 v15, v3, v12, v85
	v_fma_f32 v76, v16, v12, v14
	v_fma_f32 v77, v17, v13, v15
	s_nop 0
	v_cvt_pk_bf16_f32 v12, v76, v77
	ds_write_b32 v80, v12 offset:816
	s_waitcnt lgkmcnt(0)
	ds_read_b128 v[12:15], v79
	ds_read_b128 v[80:83], v79 offset:64
	s_waitcnt lgkmcnt(1)
	v_mfma_f32_16x16x32_bf16 v[12:15], v[12:15], v[60:63], 0
	s_waitcnt lgkmcnt(0)
	v_mfma_f32_16x16x32_bf16 v[12:15], v[80:83], v[64:67], v[12:15]
	ds_read_b128 v[80:83], v79 offset:128
	s_waitcnt lgkmcnt(0)
	v_mfma_f32_16x16x32_bf16 v[12:15], v[80:83], v[68:71], v[12:15]
	ds_read_b128 v[80:83], v79 offset:192
	s_waitcnt lgkmcnt(0)
	s_waitcnt lgkmcnt(0)
	v_mfma_f32_16x16x32_bf16 v[12:15], v[80:83], v[72:75], v[12:15]
	s_and_saveexec_b64 s[8:9], vcc
	s_cbranch_execz .LBB0_481
	v_readlane_b32 s4, v253, 46
	s_add_i32 s11, s11, s4
	s_lshl_b32 s11, s11, 1
	s_mov_b64 s[4:5], s[46:47]
	v_lshlrev_b32_e32 v0, 1, v0
	s_add_u32 s12, s4, s11
	v_add_u32_e32 v80, s95, v0
	s_addc_u32 s13, s5, 0
	v_lshl_add_u64 v[78:79], s[12:13], 0, v[0:1]
	ds_read_u16 v0, v80
	s_lshl_b64 s[6:7], s[6:7], 10
	v_lshl_add_u64 v[78:79], v[78:79], 0, s[6:7]
	s_waitcnt lgkmcnt(0)
	v_lshlrev_b32_e32 v0, 16, v0
	v_fma_f32 v0, v90, v0, v12
	v_mul_f32_e32 v12, v0, v0
	v_fmamk_f32 v12, v12, 0xbdd2d3e7, v214
	v_mul_f32_e32 v12, v0, v12
	v_exp_f32_e32 v12, v12
	s_nop 0
	v_add_f32_e32 v12, 1.0, v12
	v_rcp_f32_e32 v12, v12
	s_nop 0
	v_mul_f32_e32 v0, v0, v12
	v_cvt_pk_bf16_f32 v0, v0, v1
	global_store_short v[78:79], v0, off
	ds_read_u16 v0, v80 offset:272
	s_waitcnt lgkmcnt(0)
	v_lshlrev_b32_e32 v0, 16, v0
	v_fma_f32 v0, v90, v0, v13
	v_mul_f32_e32 v12, v0, v0
	v_fmamk_f32 v12, v12, 0xbdd2d3e7, v214
	v_mul_f32_e32 v12, v0, v12
	v_exp_f32_e32 v12, v12
	s_nop 0
	v_add_f32_e32 v12, 1.0, v12
	v_rcp_f32_e32 v12, v12
	s_nop 0
	v_mul_f32_e32 v0, v0, v12
	v_cvt_pk_bf16_f32 v0, v0, v1
	global_store_short v[78:79], v0, off offset:1024
	ds_read_u16 v0, v80 offset:544
	s_waitcnt lgkmcnt(0)
	v_lshlrev_b32_e32 v0, 16, v0
	v_fma_f32 v0, v90, v0, v14
	v_mul_f32_e32 v12, v0, v0
	v_fmamk_f32 v12, v12, 0xbdd2d3e7, v214
	v_mul_f32_e32 v12, v0, v12
	v_exp_f32_e32 v12, v12
	s_nop 0
	v_add_f32_e32 v12, 1.0, v12
	v_rcp_f32_e32 v12, v12
	s_nop 0
	v_mul_f32_e32 v0, v0, v12
	v_cvt_pk_bf16_f32 v0, v0, v1
	global_store_short v[78:79], v0, off offset:2048
	ds_read_u16 v0, v80 offset:816
	s_waitcnt lgkmcnt(0)
	v_lshlrev_b32_e32 v0, 16, v0
	v_fmac_f32_e32 v15, v90, v0
	v_mul_f32_e32 v0, v15, v15
	v_fmamk_f32 v0, v0, 0xbdd2d3e7, v214
	v_mul_f32_e32 v0, v15, v0
	v_exp_f32_e32 v0, v0
	s_nop 0
	v_add_f32_e32 v0, 1.0, v0
	v_rcp_f32_e32 v0, v0
	s_nop 0
	v_mul_f32_e32 v0, v15, v0
	v_cvt_pk_bf16_f32 v0, v0, v1
	global_store_short v[78:79], v0, off offset:3072
	s_branch .LBB0_481
